# v122 stack plus counted lgkmcnt ladder on the attention-A (k=5 copy) K-fragment reads instead of lgkmcnt(0) before the first QK MFMA
# speedup vs baseline: 1.0022x; 1.0022x over previous
.LBB0_209:
	s_mulk_i32 s21, 0x3c00
	s_mul_hi_u32 s37, s20, 0x3c00
	s_add_i32 s49, s49, 1
	s_add_i32 s37, s37, s21
	s_mulk_i32 s20, 0x3c00
	s_add_u32 s20, s30, s20
	s_addc_u32 s21, s53, s37
	s_lshl_b64 s[42:43], s[42:43], 1
	s_add_u32 s42, s62, s42
	s_addc_u32 s43, s63, s43
	s_lshl_b32 s37, s64, 14
	s_add_i32 s39, s37, 0xffffc000
	s_cmp_lg_u32 s64, 0
	s_cselect_b32 s39, s39, 0x8000
	v_lshl_add_u64 v[88:89], v[176:177], 1, s[20:21]
	s_mov_b64 s[4:5], 0x400
	s_add_i32 s39, s59, s39
	v_lshl_add_u64 v[88:89], v[88:89], 0, s[4:5]
	s_mov_b32 m0, s39
	s_nop 0
	global_load_lds_dwordx4 v[88:89], off
	v_lshl_add_u64 v[88:89], v[160:161], 1, s[42:43]
	s_add_i32 m0, s39, 0xc000
	s_nop 0
	global_load_lds_dwordx4 v[88:89], off
	v_lshl_add_u64 v[88:89], v[162:163], 1, s[20:21]
	v_lshl_add_u64 v[88:89], v[88:89], 0, s[4:5]
	s_add_i32 m0, s39, 0x400
	s_add_i32 s20, s37, 0
	global_load_lds_dwordx4 v[88:89], off
	v_lshl_add_u64 v[88:89], v[164:165], 1, s[42:43]
	s_add_i32 m0, s39, 0xc400
	s_add_i32 s20, s46, s20
	global_load_lds_dwordx4 v[88:89], off
	v_add3_u32 v100, s20, v210, v166
	v_add3_u32 v116, s20, v209, v166
	ds_read_b128 v[88:91], v100
	ds_read_b128 v[92:95], v100 offset:2048
	ds_read_b128 v[96:99], v100 offset:4096
	ds_read_b128 v[100:103], v100 offset:6144
	ds_read_b128 v[104:107], v116
	ds_read_b128 v[108:111], v116 offset:2048
	ds_read_b128 v[112:115], v116 offset:4096
	ds_read_b128 v[116:119], v116 offset:6144
	s_waitcnt lgkmcnt(7)
	v_mfma_f32_16x16x32_bf16 v[120:123], v[88:91], v[4:7], v[16:19]
	v_mfma_f32_16x16x32_bf16 v[88:91], v[88:91], v[12:15], v[20:23]
	s_waitcnt lgkmcnt(6)
	v_mfma_f32_16x16x32_bf16 v[124:127], v[92:95], v[4:7], v[16:19]
	v_mfma_f32_16x16x32_bf16 v[92:95], v[92:95], v[12:15], v[20:23]
	s_waitcnt lgkmcnt(5)
	v_mfma_f32_16x16x32_bf16 v[128:131], v[96:99], v[4:7], v[16:19]
	v_mfma_f32_16x16x32_bf16 v[96:99], v[96:99], v[12:15], v[20:23]
	s_waitcnt lgkmcnt(4)
	v_mfma_f32_16x16x32_bf16 v[132:135], v[100:103], v[4:7], v[16:19]
	v_mfma_f32_16x16x32_bf16 v[100:103], v[100:103], v[12:15], v[20:23]
	s_waitcnt lgkmcnt(3)
	v_mfma_f32_16x16x32_bf16 v[172:175], v[104:107], v[8:11], v[88:91]
	s_nop 2
	v_add_u32_e32 v88, s37, v167
	s_waitcnt lgkmcnt(2)
	v_mfma_f32_16x16x32_bf16 v[212:215], v[108:111], v[8:11], v[92:95]
	v_add_u32_e32 v89, v88, v210
	ds_read_b128 v[152:155], v89 offset:49152
	s_nop 0
	v_add_u32_e32 v92, v88, v209
	v_mfma_f32_16x16x32_bf16 v[168:171], v[104:107], v[0:3], v[120:123]
	v_mfma_f32_16x16x32_bf16 v[104:107], v[108:111], v[0:3], v[124:127]
	s_waitcnt lgkmcnt(2)
	v_mfma_f32_16x16x32_bf16 v[216:219], v[112:115], v[0:3], v[128:131]
	v_mfma_f32_16x16x32_bf16 v[220:223], v[112:115], v[8:11], v[96:99]
	s_waitcnt lgkmcnt(1)
	v_mfma_f32_16x16x32_bf16 v[224:227], v[116:119], v[0:3], v[132:135]
	v_mfma_f32_16x16x32_bf16 v[228:231], v[116:119], v[8:11], v[100:103]
	ds_read_b128 v[112:115], v92 offset:49152
	ds_read_b128 v[116:119], v89 offset:51200
	ds_read_b128 v[120:123], v92 offset:51200
	ds_read_b128 v[128:131], v89 offset:53248
	ds_read_b128 v[124:127], v92 offset:53248
	ds_read_b128 v[132:135], v89 offset:55296
	ds_read_b128 v[136:139], v92 offset:55296
	ds_read_b128 v[144:147], v89 offset:57344
	ds_read_b128 v[140:143], v92 offset:57344
	ds_read_b128 v[156:159], v89 offset:59392
	ds_read_b128 v[148:151], v92 offset:59392
	ds_read_b128 v[108:111], v89 offset:61440
	ds_read_b128 v[96:99], v92 offset:61440
	ds_read_b128 v[88:91], v89 offset:63488
	ds_read_b128 v[92:95], v92 offset:63488
	v_exp_f32_e32 v233, v168
	v_exp_f32_e32 v232, v172
	v_exp_f32_e32 v235, v104
	v_exp_f32_e32 v237, v216
	v_exp_f32_e32 v239, v224
	v_exp_f32_e32 v169, v169
	v_exp_f32_e32 v234, v212
	v_exp_f32_e32 v236, v220
	v_exp_f32_e32 v238, v228
	v_exp_f32_e32 v168, v173
	v_exp_f32_e32 v241, v105
	v_exp_f32_e32 v217, v217
	v_exp_f32_e32 v225, v225
	v_exp_f32_e32 v243, v170
	v_exp_f32_e32 v240, v213
	v_exp_f32_e32 v216, v221
	v_exp_f32_e32 v224, v229
	v_exp_f32_e32 v242, v174
	v_exp_f32_e32 v245, v106
	v_exp_f32_e32 v247, v218
	v_exp_f32_e32 v249, v226
	v_exp_f32_e32 v171, v171
	v_exp_f32_e32 v251, v107
	v_exp_f32_e32 v244, v214
	v_exp_f32_e32 v246, v222
	v_exp_f32_e32 v248, v230
	v_exp_f32_e32 v170, v175
	v_exp_f32_e32 v250, v215
	v_exp_f32_e32 v219, v219
	v_exp_f32_e32 v227, v227
	v_exp_f32_e32 v218, v223
	v_exp_f32_e32 v226, v231
	v_pk_add_f32 v[172:173], v[232:233], 0 op_sel_hi:[1,0]
	v_pk_add_f32 v[174:175], v[234:235], 0 op_sel_hi:[1,0]
	v_pk_add_f32 v[212:213], v[236:237], 0 op_sel_hi:[1,0]
	v_pk_add_f32 v[214:215], v[238:239], 0 op_sel_hi:[1,0]
	v_pk_add_f32 v[172:173], v[168:169], v[172:173]
	v_pk_add_f32 v[174:175], v[240:241], v[174:175]
	v_pk_add_f32 v[212:213], v[216:217], v[212:213]
	v_pk_add_f32 v[214:215], v[224:225], v[214:215]
	v_pk_add_f32 v[172:173], v[242:243], v[172:173]
	v_cvt_pk_bf16_f32 v104, v233, v169
	v_cvt_pk_bf16_f32 v105, v243, v171
	v_cvt_pk_bf16_f32 v106, v235, v241
	v_cvt_pk_bf16_f32 v107, v245, v251
	v_pk_add_f32 v[174:175], v[244:245], v[174:175]
	v_pk_add_f32 v[212:213], v[246:247], v[212:213]
	v_pk_add_f32 v[214:215], v[248:249], v[214:215]
	v_pk_add_f32 v[172:173], v[170:171], v[172:173]
	v_cvt_pk_bf16_f32 v168, v232, v168
	v_cvt_pk_bf16_f32 v169, v242, v170
	v_cvt_pk_bf16_f32 v170, v234, v240
	v_cvt_pk_bf16_f32 v171, v244, v250
	v_pk_add_f32 v[174:175], v[250:251], v[174:175]
	v_pk_add_f32 v[212:213], v[218:219], v[212:213]
	v_pk_add_f32 v[214:215], v[226:227], v[214:215]
	s_waitcnt lgkmcnt(0)
	v_mfma_f32_16x16x32_bf16 v[84:87], v[152:155], v[104:107], v[84:87]
	v_add_f32_e64 v172, v172, v174
	v_add_f32_e64 v173, v173, v175
	v_pk_add_f32 v[174:175], v[212:213], v[214:215]
	v_cvt_pk_bf16_f32 v100, v237, v217
	v_mfma_f32_16x16x32_bf16 v[80:83], v[152:155], v[168:171], v[80:83]
	v_add_f32_e64 v172, v172, v174
	v_add_f32_e64 v173, v173, v175
	v_cvt_pk_bf16_f32 v101, v247, v219
	v_cvt_pk_bf16_f32 v102, v239, v225
	v_mfma_f32_16x16x32_bf16 v[76:79], v[116:119], v[104:107], v[76:79]
	v_cvt_pk_bf16_f32 v103, v249, v227
	v_pk_add_f32 v[182:183], v[182:183], v[172:173]
	v_cvt_pk_bf16_f32 v172, v236, v216
	v_mfma_f32_16x16x32_bf16 v[72:75], v[116:119], v[168:171], v[72:75]
	v_cvt_pk_bf16_f32 v173, v246, v218
	v_cvt_pk_bf16_f32 v174, v238, v224
	v_cvt_pk_bf16_f32 v175, v248, v226
	v_mfma_f32_16x16x32_bf16 v[68:71], v[128:131], v[104:107], v[68:71]
	s_add_i32 s20, s64, 1
	s_cmp_lg_u32 s64, 2
	s_cselect_b32 s64, s20, 0
	v_mfma_f32_16x16x32_bf16 v[64:67], v[128:131], v[168:171], v[64:67]
	s_add_u32 s40, s40, 64
	s_addc_u32 s41, s41, 0
	s_cmp_eq_u32 s49, 34
	v_mfma_f32_16x16x32_bf16 v[60:63], v[132:135], v[104:107], v[60:63]
	v_mfma_f32_16x16x32_bf16 v[56:59], v[132:135], v[168:171], v[56:59]
	v_mfma_f32_16x16x32_bf16 v[52:55], v[144:147], v[104:107], v[52:55]
	v_mfma_f32_16x16x32_bf16 v[48:51], v[144:147], v[168:171], v[48:51]
	v_mfma_f32_16x16x32_bf16 v[44:47], v[156:159], v[104:107], v[44:47]
	v_mfma_f32_16x16x32_bf16 v[40:43], v[156:159], v[168:171], v[40:43]
	v_mfma_f32_16x16x32_bf16 v[36:39], v[108:111], v[104:107], v[36:39]
	v_mfma_f32_16x16x32_bf16 v[24:27], v[108:111], v[168:171], v[24:27]
	v_mfma_f32_16x16x32_bf16 v[32:35], v[88:91], v[104:107], v[32:35]
	v_mfma_f32_16x16x32_bf16 v[28:31], v[88:91], v[168:171], v[28:31]
	v_mfma_f32_16x16x32_bf16 v[84:87], v[112:115], v[100:103], v[84:87]
	v_mfma_f32_16x16x32_bf16 v[80:83], v[112:115], v[172:175], v[80:83]
	v_mfma_f32_16x16x32_bf16 v[76:79], v[120:123], v[100:103], v[76:79]
	v_mfma_f32_16x16x32_bf16 v[72:75], v[120:123], v[172:175], v[72:75]
	v_mfma_f32_16x16x32_bf16 v[68:71], v[124:127], v[100:103], v[68:71]
	v_mfma_f32_16x16x32_bf16 v[64:67], v[124:127], v[172:175], v[64:67]
	v_mfma_f32_16x16x32_bf16 v[60:63], v[136:139], v[100:103], v[60:63]
	v_mfma_f32_16x16x32_bf16 v[56:59], v[136:139], v[172:175], v[56:59]
	v_mfma_f32_16x16x32_bf16 v[52:55], v[140:143], v[100:103], v[52:55]
	v_mfma_f32_16x16x32_bf16 v[48:51], v[140:143], v[172:175], v[48:51]
	v_mfma_f32_16x16x32_bf16 v[44:47], v[148:151], v[100:103], v[44:47]
	v_mfma_f32_16x16x32_bf16 v[40:43], v[148:151], v[172:175], v[40:43]
	v_mfma_f32_16x16x32_bf16 v[36:39], v[96:99], v[100:103], v[36:39]
	v_mfma_f32_16x16x32_bf16 v[24:27], v[96:99], v[172:175], v[24:27]
	v_mfma_f32_16x16x32_bf16 v[32:35], v[92:95], v[100:103], v[32:35]
	v_mfma_f32_16x16x32_bf16 v[28:31], v[92:95], v[172:175], v[28:31]
	s_cbranch_scc1 .LBB0_214
